# kernel prologue: kernarg scalar loads batched (8 serialized round trips -> 2) plus scalar-cache prefetch of the kernarg lines first touched after the first grid barrier
# baseline (speedup 1.0000x reference)
.LBB0_2:
	s_or_b64 exec, exec, s[4:5]

	s_waitcnt lgkmcnt(0)
	s_barrier
	s_getreg_b32 s3, hwreg(HW_REG_XCC_ID, 0, 4)
	v_writelane_b32 v253, s12, 3
	s_and_b32 s3, s3, 15
	s_nop 0
	v_writelane_b32 v253, s13, 4
	v_writelane_b32 v253, s14, 5
	v_writelane_b32 v253, s15, 6
	v_writelane_b32 v253, s16, 7
	v_writelane_b32 v253, s17, 8
	v_writelane_b32 v253, s18, 9
	v_writelane_b32 v253, s19, 10
	v_writelane_b32 v253, s20, 11
	v_writelane_b32 v253, s21, 12
	v_writelane_b32 v253, s22, 13
	v_writelane_b32 v253, s23, 14
	v_writelane_b32 v253, s24, 15
	v_writelane_b32 v253, s25, 16
	v_writelane_b32 v253, s26, 17
	v_writelane_b32 v253, s27, 18


	v_writelane_b32 v253, s56, 19
	s_nop 1
	v_writelane_b32 v253, s57, 20
	v_writelane_b32 v253, s58, 21
	v_writelane_b32 v253, s59, 22
	v_writelane_b32 v253, s60, 23
	v_writelane_b32 v253, s61, 24
	v_writelane_b32 v253, s62, 25
	v_writelane_b32 v253, s63, 26
	v_writelane_b32 v253, s64, 27
	v_writelane_b32 v253, s65, 28
	v_writelane_b32 v253, s66, 29
	v_writelane_b32 v253, s67, 30
	v_writelane_b32 v253, s68, 31
	v_writelane_b32 v253, s69, 32
	v_writelane_b32 v253, s70, 33
	v_writelane_b32 v253, s71, 34


	v_writelane_b32 v253, s72, 35
	s_nop 1
	v_writelane_b32 v253, s73, 36
	v_writelane_b32 v253, s74, 37
	v_writelane_b32 v253, s75, 38
	v_writelane_b32 v253, s76, 39
	v_writelane_b32 v253, s77, 40
	v_writelane_b32 v253, s78, 41
	v_writelane_b32 v253, s79, 42
	v_writelane_b32 v253, s80, 43
	v_writelane_b32 v253, s81, 44
	v_writelane_b32 v253, s82, 45
	v_writelane_b32 v253, s83, 46
	v_writelane_b32 v253, s84, 47
	v_writelane_b32 v253, s85, 48
	v_writelane_b32 v253, s86, 49
	v_writelane_b32 v253, s87, 50
	s_load_dwordx16 s[56:71], s[0:1], 0x140
	s_load_dwordx16 s[72:87], s[0:1], 0x180
	s_load_dwordx8 s[28:35], s[0:1], 0x200
	s_load_dwordx8 s[88:95], s[0:1], 0x220
	s_load_dwordx16 s[12:27], s[0:1], 0x0
	s_load_dwordx4 s[96:99], s[0:1], 0x100
	s_load_dwordx2 s[100:101], s[0:1], 0x1c0
	s_load_dwordx2 s[36:37], s[0:1], 0x2d8
	s_waitcnt lgkmcnt(0)
	v_writelane_b32 v253, s56, 51
	s_nop 1
	v_writelane_b32 v253, s57, 52
	v_writelane_b32 v253, s58, 53
	v_writelane_b32 v253, s59, 54
	v_writelane_b32 v253, s60, 55
	v_writelane_b32 v253, s61, 56
	v_writelane_b32 v253, s62, 57
	v_writelane_b32 v253, s63, 58
	v_writelane_b32 v253, s64, 59
	v_writelane_b32 v253, s65, 60
	v_writelane_b32 v253, s66, 61
	v_writelane_b32 v254, s69, 0
	v_writelane_b32 v253, s67, 62
	v_writelane_b32 v254, s70, 1
	v_writelane_b32 v253, s68, 63
	v_writelane_b32 v254, s71, 2

	v_writelane_b32 v254, s3, 3

	v_writelane_b32 v254, s72, 4
	s_nop 1
	v_writelane_b32 v254, s73, 5
	v_writelane_b32 v254, s74, 6
	v_writelane_b32 v254, s75, 7
	v_writelane_b32 v254, s76, 8
	v_writelane_b32 v254, s77, 9
	v_writelane_b32 v254, s78, 10
	v_writelane_b32 v254, s79, 11
	v_writelane_b32 v254, s80, 12
	v_writelane_b32 v254, s81, 13
	v_writelane_b32 v254, s82, 14
	v_writelane_b32 v254, s83, 15
	v_writelane_b32 v254, s84, 16
	v_writelane_b32 v254, s85, 17
	v_writelane_b32 v254, s86, 18
	v_writelane_b32 v254, s87, 19


	v_writelane_b32 v254, s28, 20
	s_nop 1
	v_writelane_b32 v254, s29, 21
	v_writelane_b32 v254, s30, 22
	v_writelane_b32 v254, s31, 23
	v_writelane_b32 v254, s32, 24
	v_writelane_b32 v254, s33, 25
	v_writelane_b32 v254, s34, 26
	v_writelane_b32 v254, s35, 27
	v_writelane_b32 v254, s88, 28
	v_writelane_b32 v254, s89, 29
	v_writelane_b32 v254, s90, 30
	v_writelane_b32 v254, s91, 31
	v_writelane_b32 v254, s92, 32
	v_writelane_b32 v254, s93, 33
	v_writelane_b32 v254, s94, 34
	v_writelane_b32 v254, s95, 35
	s_mov_b64 s[4:5], exec
	v_readlane_b32 s6, v253, 1
	v_readlane_b32 s7, v253, 2
	s_and_b64 s[6:7], s[4:5], s[6:7]
	s_mov_b64 exec, s[6:7]
	s_cbranch_execz .LBB0_5
	s_mov_b64 s[6:7], exec
	v_mbcnt_lo_u32_b32 v1, s6, 0
	v_mbcnt_hi_u32_b32 v1, s7, v1
	v_cmp_eq_u32_e32 vcc, 0, v1
	s_and_b64 s[10:11], exec, vcc
	s_mov_b64 exec, s[10:11]
	s_cbranch_execz .LBB0_5
	v_readlane_b32 s3, v254, 3
	s_lshl_b32 s3, s3, 8
	s_bcnt1_i32_b64 s6, s[6:7]
	v_mov_b32_e32 v1, s3
	v_mov_b32_e32 v2, s6
	global_atomic_add v1, v2, s[54:55] offset:1024
